# input-projection and FFN-up GEMMs: each XCD walks its chunk of the tile order from the next multiple of 4 (windows of 32 tiles cover 8 whole weight tiles instead of 9)
# baseline (speedup 1.0000x reference)
;     __host__ __device__ bool next(int i, Unit& u) const {
;         const long L = (long)i * G + c; if (L >= nwg) return false;
;         int wgid = (int)L; { const int q = nwg / NXCD, r = nwg % NXCD, xcd = wgid % NXCD, off = wgid / NXCD; wgid = (xcd < r ? xcd * (q + 1) : r * (q + 1) + (xcd - r) * q) + off; }
;         const int nig = WGM * nN, gid = wgid / nig, fm = gid * WGM, gsz = (nM - fm) < WGM ? (nM - fm) : WGM;
;         u.pm = fm + ((wgid % nig) % gsz); u.pn = (wgid % nig) / gsz; return true;
.LBB0_4203:
	s_ashr_i32 s0, s46, 31
	s_lshr_b32 s0, s0, 29
	s_add_i32 s0, s46, s0
	v_readlane_b32 s16, v253, 0
	s_ashr_i32 s14, s0, 3
	s_and_b32 s0, s0, -8
	v_readlane_b32 s17, v253, 1
	s_sub_i32 s15, s46, s0
	s_ashr_i32 s17, s16, 31
	s_cmp_eq_u32 s52, 15
	s_cselect_b64 s[0:1], -1, 0
	v_writelane_b32 v253, s0, 33
	s_cmp_eq_u32 s52, 14
	s_mul_i32 s9, s15, 0x41
	v_writelane_b32 v253, s1, 34
	s_cselect_b64 s[0:1], -1, 0
	v_writelane_b32 v253, s0, 35
	s_cmp_eq_u32 s52, 13
	s_mov_b32 s27, 0
	v_writelane_b32 v253, s1, 36
	s_cselect_b64 s[0:1], -1, 0
	v_writelane_b32 v253, s0, 37
	s_cmp_eq_u32 s52, 12
	s_waitcnt vmcnt(1)
	v_mov_b32_e32 v32, 0
	v_writelane_b32 v253, s1, 38
	s_cselect_b64 s[0:1], -1, 0
	v_writelane_b32 v253, s0, 39
	s_cmp_eq_u32 s52, 11
	v_mov_b32_e32 v252, 0xff800000
	v_writelane_b32 v253, s1, 40
	s_cselect_b64 s[0:1], -1, 0
	v_writelane_b32 v253, s0, 41
	s_cmp_eq_u32 s52, 10
	s_mov_b32 s26, 2
	v_writelane_b32 v253, s1, 42
	s_cselect_b64 s[0:1], -1, 0
	v_writelane_b32 v253, s0, 43
	s_cmp_eq_u32 s52, 9
	s_movk_i32 s33, 0x88
	v_writelane_b32 v253, s1, 44
	s_cselect_b64 s[0:1], -1, 0
	v_writelane_b32 v253, s0, 45
	s_cmp_eq_u32 s52, 8
	s_movk_i32 s64, 0x190
	v_writelane_b32 v253, s1, 46
	s_cselect_b64 s[0:1], -1, 0
	v_writelane_b32 v253, s0, 47
	s_cmp_eq_u32 s52, 7
	s_mov_b64 s[24:25], 0x80
	v_writelane_b32 v253, s1, 48
	s_cselect_b64 s[0:1], -1, 0
	v_writelane_b32 v253, s0, 49
	s_cmp_eq_u32 s52, 6
	s_nop 0
	v_writelane_b32 v253, s1, 50
	s_cselect_b64 s[0:1], -1, 0
	v_writelane_b32 v253, s0, 51
	s_cmp_eq_u32 s52, 5
	s_nop 0
	v_writelane_b32 v253, s1, 52
	s_cselect_b64 s[0:1], -1, 0
	v_writelane_b32 v253, s0, 53
	s_cmp_eq_u32 s52, 4
	s_nop 0
	v_writelane_b32 v253, s1, 54
	s_cselect_b64 s[0:1], -1, 0
	v_writelane_b32 v253, s0, 55
	s_cmp_eq_u32 s52, 3
	s_nop 0
	v_writelane_b32 v253, s1, 56
	s_cselect_b64 s[0:1], -1, 0
	v_writelane_b32 v253, s0, 57
	s_cmp_eq_u32 s52, 2
	s_nop 0
	v_writelane_b32 v253, s1, 58
	s_cselect_b64 s[0:1], -1, 0
	v_writelane_b32 v253, s0, 59
	s_cmp_eq_u32 s52, 1
	s_nop 0
	v_writelane_b32 v253, s1, 60
	s_cselect_b64 s[0:1], -1, 0
	v_writelane_b32 v253, s0, 61
	s_cmp_eq_u32 s52, 0
	s_nop 0
	v_writelane_b32 v253, s1, 62
	s_cselect_b64 s[0:1], -1, 0
	v_writelane_b32 v253, s0, 63
	s_lshl_b32 s18, s46, 3
	s_lshl_b32 s22, s16, 3
	v_writelane_b32 v254, s1, 0
	s_lshl_b32 s0, s52, 6
	v_writelane_b32 v254, s0, 1
	s_lshl_b32 s0, s16, 4
	v_writelane_b32 v253, s0, 25
	s_lshl_b32 s0, s16, 5
	s_add_i32 s6, s46, 0x88
	s_add_i32 s7, s46, 0x48
	s_cmpk_lt_i32 s16, 0x156
	v_writelane_b32 v254, s0, 2
	s_cselect_b64 s[0:1], -1, 0
	v_writelane_b32 v254, s0, 3
	s_add_i32 s8, s46, 0xc8
	v_writelane_b32 v253, s17, 17
	v_writelane_b32 v254, s1, 4
	s_and_b32 s0, s16, 7
	s_cmp_eq_u32 s0, 0
	s_cselect_b64 s[0:1], -1, 0
	v_writelane_b32 v254, s0, 5
	s_nop 1
	v_writelane_b32 v254, s1, 6
	s_and_b32 s0, s46, 7
	s_ashr_i32 s1, s16, 3
	s_mul_i32 s3, s1, s0
	s_ashr_i32 s0, s46, 3
	s_add_i32 s3, s3, s0
	s_cmpk_lt_i32 s46, 0x800
	s_cselect_b64 s[0:1], -1, 0
	v_writelane_b32 v254, s0, 7
	s_nop 1
	v_writelane_b32 v254, s1, 8
	s_and_b64 s[0:1], s[0:1], exec
	s_cselect_b32 s0, s46, 0
	s_ashr_i32 s1, s0, 31
	s_lshl_b64 s[0:1], s[0:1], 14
	v_writelane_b32 v254, s0, 9
	s_nop 1
	v_writelane_b32 v254, s1, 10
	s_lshl_b32 s1, s46, 6
	s_and_b32 s0, s18, 0xffffe000
	v_writelane_b32 v254, s1, 11
	s_and_b32 s1, s1, 0x1fc0
	s_or_b32 s2, s0, s1
	s_bfe_u32 s1, s46, 0x30007
	s_lshl_b32 s0, s1, 6
	s_lshl_b32 s1, s1, 7
	s_cmpk_lt_i32 s46, 0x200
	s_cselect_b64 s[4:5], -1, 0
	v_writelane_b32 v254, s4, 12
	s_nop 1
	v_writelane_b32 v254, s5, 13
	s_lshl_b32 s4, s15, 6
	s_cmpk_lt_i32 s46, 0x100
	s_cselect_b64 s[10:11], -1, 0
	v_writelane_b32 v254, s10, 14
	s_cmpk_lt_i32 s46, 0x1658
	s_nop 0
	v_writelane_b32 v254, s11, 15
	s_cselect_b64 s[10:11], -1, 0
	v_writelane_b32 v254, s10, 16
	s_lshl_b32 s5, s46, 9
	s_nop 0
	v_writelane_b32 v254, s11, 17
	v_writelane_b32 v254, s5, 18
	s_lshl_b32 s5, s16, 9
	s_cmpk_lt_i32 s46, 0x400
	v_writelane_b32 v254, s5, 19
	s_cselect_b64 s[10:11], -1, 0
	s_lshl_b32 s5, s15, 7
	v_writelane_b32 v254, s10, 20
	s_cmp_lt_i32 s15, 0
	s_cselect_b32 s4, s9, s4
	v_writelane_b32 v254, s11, 21
	s_mul_i32 s10, s15, 0x81
	s_movk_i32 s9, 0x2cc
	s_cselect_b32 s9, s9, 0x2cb
	s_cselect_b32 s10, s10, s5
	s_add_i32 s4, s4, s14
	s_ashr_i32 s5, s4, 31
	s_lshr_b32 s5, s5, 27
	s_add_i32 s5, s4, s5
	s_ashr_i32 s11, s5, 5
	s_and_b32 s5, s5, 0xffe0
	s_sub_i32 s5, s4, s5
	s_bfe_i32 s4, s5, 0x80000
	s_bfe_u32 s4, s4, 0x2000d
	s_add_i32 s12, s5, s4
	s_bfe_i32 s4, s12, 0x80000
	s_and_b32 s12, s12, 0xfc
	s_sub_i32 s5, s5, s12
	s_lshl_b32 s11, s11, 2
	s_sext_i32_i16 s13, s4
	s_sext_i32_i8 s5, s5
	s_add_i32 s20, s11, s5
	s_ashr_i32 s5, s13, 2
	v_writelane_b32 v254, s5, 22
	s_mov_b32 s12, s20
	s_lshr_b32 s4, s13, 2
	s_ashr_i32 s21, s20, 31
	v_writelane_b32 v254, s12, 23
	s_bfe_i64 s[4:5], s[4:5], 0x100000
	s_lshl_b64 s[4:5], s[4:5], 20
	v_writelane_b32 v254, s13, 24
	s_lshl_b64 s[12:13], s[20:21], 20
	v_writelane_b32 v254, s12, 25
	s_mov_b32 s21, 0x18480
	s_mov_b32 s20, 0x41000000
	v_writelane_b32 v254, s13, 26
	v_writelane_b32 v254, s4, 27
	s_nop 1
	v_writelane_b32 v254, s5, 28
	s_mul_i32 s4, s15, s9
	s_sub_i32 s5, 0, s4
	s_and_b32 s5, s5, 3
	s_add_i32 s5, s5, s14
	s_cmp_ge_u32 s5, s9
	s_cselect_b32 s9, s9, 0
	s_sub_i32 s5, s5, s9
	s_add_i32 s4, s4, s5
	s_mul_hi_i32 s5, s4, 0x2e8ba2e9
	s_lshr_b32 s9, s5, 31
	s_ashr_i32 s5, s5, 5
	s_add_i32 s5, s5, s9
	s_mul_i32 s9, s5, 0xb0
	s_lshl_b32 s11, s5, 2
	s_sub_i32 s5, 0x82, s11
	s_sub_i32 s9, s4, s9
	s_add_i32 s4, s10, s14
	s_min_u32 s12, s5, 4
	s_ashr_i32 s5, s4, 31
	v_writelane_b32 v254, s14, 29
	s_lshr_b32 s5, s5, 27
	s_abs_i32 s14, s16
; __device__ __forceinline__ int opaque_tid(int wave_s) { int t; asm volatile("v_mbcnt_lo_u32_b32 %0, -1, 0\n\tv_mbcnt_hi_u32_b32 %0, -1, %0" : "=v"(t)); return (wave_s << 6) | t; }
;     __host__ __device__ bool next(int i, Unit& u) const {
;         const long L = (long)i * G + c; if (L >= nwg) return false;
;         int wgid = (int)L; { const int q = nwg / NXCD, r = nwg % NXCD, xcd = wgid % NXCD, off = wgid / NXCD; wgid = (xcd < r ? xcd * (q + 1) : r * (q + 1) + (xcd - r) * q) + off; }
;         const int nig = WGM * nN, gid = wgid / nig, fm = gid * WGM, gsz = (nM - fm) < WGM ? (nM - fm) : WGM;
;         u.pm = fm + ((wgid % nig) % gsz); u.pn = (wgid % nig) / gsz; return true;
; __global__ void __launch_bounds__(512, 2) hse_fwd(Params P) {
;     ...
;               { const int tid = opaque_tid(wave_s); pg8::Gemm gm{ckva, wt + WT_UK, gr.nkv, 1024, 256, 256, 256}; pg8::StaticOrder S; S.init(gm.M, gm.N, G, (bid + 136) % G);
;                 EpiPlain<1024> E{knope}; pg8::gemm_phase<EpiPlain<1024>>(tid, lds, gm, S, E); }
;               { const int tid = opaque_tid(wave_s); pg8::Gemm gm{wt + WT_UV, ckva, 1024, gr.nkv, 256, 256, 256}; pg8::StaticOrder S; S.init(gm.M, gm.N, G, (bid + 72) % G);
;                 EpiPlain<VT_LD> E{vtb}; pg8::gemm_phase<EpiPlain<VT_LD>>(tid, lds, gm, S, E); }
;               __syncthreads();
;               { const int tid = opaque_tid(wave_s); const int lane = tid & 63; const int nun = GNB * 8 * 128;
;                   const int uqu = (gr.nxr / 256) * 6, nl = uqu - G, nh = G - nl; const bool bal = nl > 0 && nh > 0 && 6 * G <= nun;
	s_add_i32 s5, s4, s5
	v_cvt_f32_u32_e32 v0, s14
	s_ashr_i32 s10, s5, 5
	s_and_b32 s5, s5, 0xffe0
	s_sub_i32 s4, s4, s5
	s_bfe_i32 s5, s4, 0x80000
	s_bfe_u32 s5, s5, 0x2000d
	v_rcp_iflag_f32_e32 v0, v0
	s_add_i32 s5, s4, s5
	s_bfe_i32 s13, s5, 0x80000
	s_and_b32 s5, s5, 0xfc
	s_sub_i32 s4, s4, s5
	s_lshl_b32 s10, s10, 2
	s_sext_i32_i8 s4, s4
	v_mul_f32_e32 v0, 0x4f7ffffe, v0
	s_sext_i32_i16 s13, s13
	s_add_i32 s4, s10, s4
	v_cvt_u32_f32_e32 v0, v0
	v_writelane_b32 v254, s4, 30
	s_ashr_i32 s4, s13, 2
	v_writelane_b32 v254, s4, 31
	v_writelane_b32 v254, s15, 32
	s_lshr_b32 s4, s15, 31
	v_writelane_b32 v254, s4, 33
	s_ashr_i32 s4, s6, 31
	s_abs_i32 s5, s6
	s_sub_i32 s6, 0, s14
	v_readfirstlane_b32 s10, v0
	s_mul_i32 s6, s6, s10
	s_mul_hi_u32 s6, s10, s6
	s_add_i32 s10, s10, s6
	s_mul_hi_u32 s6, s5, s10
	s_mul_i32 s6, s6, s14
	s_sub_i32 s5, s5, s6
	s_sub_i32 s6, s5, s14
	s_cmp_ge_u32 s5, s14
	s_cselect_b32 s5, s6, s5
	s_sub_i32 s6, s5, s14
	s_cmp_ge_u32 s5, s14
	s_cselect_b32 s5, s6, s5
	s_xor_b32 s5, s5, s4
	s_sub_i32 s13, s5, s4
	s_ashr_i32 s6, s13, 31
	s_lshr_b32 s4, s6, 29
	s_add_i32 s4, s13, s4
	s_ashr_i32 s5, s4, 3
	s_and_b32 s4, s4, -8
	s_sub_i32 s4, s13, s4
	v_writelane_b32 v254, s5, 34
	s_cmp_lt_i32 s4, 0
	v_writelane_b32 v254, s4, 35
	s_cselect_b64 s[4:5], -1, 0
	v_writelane_b32 v254, s4, 36
	v_cvt_f32_ubyte0_e32 v1, s12
	v_cvt_f32_i32_e32 v0, s9
	v_writelane_b32 v254, s5, 37
	s_abs_i32 s5, s7
	s_ashr_i32 s4, s7, 31
	s_mul_hi_u32 s7, s5, s10
	s_mul_i32 s7, s7, s14
	s_sub_i32 s5, s5, s7
	s_sub_i32 s7, s5, s14
	s_cmp_ge_u32 s5, s14
	s_cselect_b32 s5, s7, s5
	s_sub_i32 s7, s5, s14
	s_cmp_ge_u32 s5, s14
	s_cselect_b32 s5, s7, s5
	s_xor_b32 s5, s5, s4
	s_sub_i32 s15, s5, s4
	s_ashr_i32 s7, s15, 31
	s_lshr_b32 s4, s7, 29
	s_add_i32 s4, s15, s4
	s_ashr_i32 s5, s4, 3
	s_and_b32 s4, s4, -8
	s_sub_i32 s4, s15, s4
	v_writelane_b32 v254, s5, 38
	s_cmp_lt_i32 s4, 0
	v_writelane_b32 v254, s4, 39
	s_cselect_b64 s[4:5], -1, 0
	v_writelane_b32 v254, s4, 40
	v_rcp_iflag_f32_e32 v2, v1
	s_nop 0
	v_writelane_b32 v254, s5, 41
	s_abs_i32 s4, s8
	s_mul_hi_u32 s5, s4, s10
	s_mul_i32 s5, s5, s14
	s_sub_i32 s4, s4, s5
	s_ashr_i32 s5, s8, 31
	s_sub_i32 s8, s4, s14
	s_cmp_ge_u32 s4, s14
	s_cselect_b32 s4, s8, s4
	s_sub_i32 s8, s4, s14
	s_cmp_ge_u32 s4, s14
	s_cselect_b32 s4, s8, s4
	s_xor_b32 s4, s4, s5
	s_sub_i32 s4, s4, s5
	s_cmpk_lt_i32 s4, 0x800
	v_writelane_b32 v254, s4, 42
	s_cselect_b32 s4, s4, -1
	v_writelane_b32 v254, s4, 43
	s_lshr_b32 s4, s10, 24
	s_mul_i32 s4, s4, s14
	s_sub_i32 s4, 0x100, s4
	s_sub_i32 s5, s4, s14
	s_cmp_ge_u32 s4, s14
	s_cselect_b32 s4, s5, s4
	s_sub_i32 s5, s4, s14
	s_cmp_ge_u32 s4, s14
	s_cselect_b32 s4, s5, s4
	s_cmp_eq_u32 s4, 0
	s_cselect_b64 s[4:5], -1, 0
	v_writelane_b32 v254, s4, 44
	v_mul_f32_e32 v2, v0, v2
	v_trunc_f32_e32 v2, v2
	v_writelane_b32 v254, s5, 45
	s_lshr_b32 s4, s10, 23
	s_mul_i32 s4, s4, s14
	s_sub_i32 s4, 0x200, s4
	s_sub_i32 s5, s4, s14
	s_cmp_ge_u32 s4, s14
	s_cselect_b32 s4, s5, s4
	s_sub_i32 s5, s4, s14
	s_cmp_ge_u32 s4, s14
	s_cselect_b32 s4, s5, s4
	s_cmp_eq_u32 s4, 0
	v_fma_f32 v0, -v2, v1, v0
	s_cselect_b32 s3, s3, s46
	v_cmp_ge_f32_e64 s[4:5], |v0|, v1
	v_cvt_i32_f32_e32 v0, v2
	v_writelane_b32 v254, s3, 46
	s_ashr_i32 s3, s9, 30
	s_or_b32 s3, s3, 1
	s_and_b64 s[4:5], s[4:5], exec
	s_cselect_b32 s3, s3, 0
	v_readfirstlane_b32 s4, v0
	s_add_i32 s3, s4, s3
	s_mul_i32 s4, s3, s12
	s_sub_i32 s4, s9, s4
	s_sext_i32_i16 s4, s4
	s_add_i32 s4, s11, s4
	v_writelane_b32 v254, s4, 47
	v_writelane_b32 v254, s18, 48
	s_ashr_i32 s4, s18, 31
	v_writelane_b32 v254, s4, 49
	s_add_u32 s4, s16, s13
	v_writelane_b32 v254, s13, 50
	s_addc_u32 s5, s17, s6
	v_writelane_b32 v254, s4, 51
	s_mov_b32 s6, s27
	s_nop 0
	v_writelane_b32 v254, s5, 52
	s_add_u32 s4, s16, s15
	v_writelane_b32 v254, s15, 53
	s_addc_u32 s5, s17, s7
	v_writelane_b32 v254, s4, 54
	s_lshl_b32 s0, s0, 1
	s_ashr_i32 s23, s22, 31
	v_writelane_b32 v254, s5, 55
	s_mul_hi_i32 s4, s2, 0x3800
	v_writelane_b32 v254, s4, 56
	s_mulk_i32 s2, 0x3800
	v_writelane_b32 v254, s2, 57
	s_sext_i32_i16 s2, s3
	v_writelane_b32 v254, s2, 58
	v_readlane_b32 s2, v253, 9
	s_sub_i32 s2, s46, s2
	s_add_i32 s3, 0, 0x200c8
	v_writelane_b32 v254, s2, 59
	s_add_i32 s2, s46, 0xfffffc00
	v_writelane_b32 v254, s2, 60
	s_add_i32 s2, s46, 0xfffffd00
	v_writelane_b32 v254, s2, 61
	s_lshl_b32 s2, s16, 6
	v_writelane_b32 v253, s2, 21
	s_lshl_b32 s2, s46, 1
	v_writelane_b32 v254, s2, 62
	s_lshl_b32 s2, s16, 1
	v_writelane_b32 v254, s2, 63
	s_lshl_b32 s2, s46, 2
	v_writelane_b32 v255, s2, 0
	s_lshl_b32 s2, s16, 2
	v_writelane_b32 v255, s2, 1
	s_add_i32 s2, 0, 0x20148
	v_writelane_b32 v255, s2, 2
	s_add_i32 s2, 0, 0x20000
	v_writelane_b32 v255, s2, 3
	s_add_i32 s2, 0, 0x20004
	v_writelane_b32 v255, s2, 4
	s_add_i32 s2, 0, 0x20140
	v_writelane_b32 v255, s2, 5
	s_add_i32 s2, 0, 0x200b0
	v_writelane_b32 v255, s2, 6
	s_add_i32 s2, 0, 0x20060
	v_writelane_b32 v255, s2, 7
	v_writelane_b32 v255, s3, 8
	s_add_i32 s3, 0, 0x20070
	v_writelane_b32 v255, s3, 9
	v_writelane_b32 v255, s0, 10
	s_add_i32 s2, 0, 0x15000
	v_writelane_b32 v253, s2, 19
	v_writelane_b32 v255, s1, 11
	s_lshl_b32 s0, s1, 1
	s_add_i32 s3, 0, 0x15400
	v_writelane_b32 v255, s0, 12
	v_writelane_b32 v253, s3, 31
	s_mov_b32 s2, 0xc800
	v_writelane_b32 v255, s1, 13
	s_add_i32 s0, 0, 0x200d0
	v_writelane_b32 v253, s0, 27
	s_add_i32 s0, 0, 0x20080
	v_writelane_b32 v255, s0, 14
	s_add_i32 s0, 0, 0x200f8
	v_writelane_b32 v255, s0, 15
	s_add_i32 s0, 0, 0x20048
	v_writelane_b32 v255, s0, 16
	s_add_i32 s0, 0, 0x20040
	v_writelane_b32 v255, s0, 17
	s_add_i32 s0, 0, 0x20118
	v_writelane_b32 v255, s0, 18
	s_add_i32 s0, 0, 0x20088
	v_writelane_b32 v255, s0, 19
	s_add_i32 s0, 0, 0x20130
	v_writelane_b32 v255, s0, 20
	s_add_i32 s0, 0, 0x200a8
	v_writelane_b32 v255, s0, 21
	s_lshl_b64 s[0:1], s[22:23], 12
	v_writelane_b32 v255, s0, 22
	s_movk_i32 s3, 0xf800
	s_mov_b64 s[4:5], -1
	v_writelane_b32 v255, s1, 23
	s_mov_b32 s0, s22
	v_writelane_b32 v253, s0, 9
	s_nop 1
	v_writelane_b32 v253, s1, 10
	s_lshl_b64 s[0:1], s[22:23], 13
	v_writelane_b32 v255, s0, 24
	v_writelane_b32 v253, s46, 4
	s_mov_b64 s[22:23], 0x100
	v_writelane_b32 v255, s1, 25
	s_mov_b64 s[0:1], 0
	v_writelane_b32 v255, s0, 26
	v_writelane_b32 v253, s47, 5
	s_nop 0
	v_writelane_b32 v255, s1, 27
	s_branch .LBB0_4207

;     __host__ __device__ bool next(int i, Unit& u) const {
;         const long L = (long)i * G + c; if (L >= nwg) return false;
;         int wgid = (int)L; { const int q = nwg / NXCD, r = nwg % NXCD, xcd = wgid % NXCD, off = wgid / NXCD; wgid = (xcd < r ? xcd * (q + 1) : r * (q + 1) + (xcd - r) * q) + off; }
;         const int nig = WGM * nN, gid = wgid / nig, fm = gid * WGM, gsz = (nM - fm) < WGM ? (nM - fm) : WGM;
;         u.pm = fm + ((wgid % nig) % gsz); u.pn = (wgid % nig) / gsz; return true;
; __global__ void __launch_bounds__(512, 2) hse_fwd(Params P) {
;     ...
;             { pg8::Gemm gm{hbuf + (size_t)gr.xr0 * DM, wt + WT_IN, gr.nxr, NPROJ_ALL, 2048, 2048, 2048}; pg8::StaticOrder S; S.init(gm.M, gm.N, G, bid);
;               EpiProj E{proj, gatebuf}; pg8::gemm_phase<EpiProj>(tid, lds, gm, S, E); }
.LBB0_4213:
	s_andn2_b64 vcc, exec, s[0:1]
	s_cbranch_vccnz .LBB0_4430
	v_readlane_b32 s0, v253, 8
	s_barrier
	s_waitcnt vmcnt(0)
	v_mbcnt_lo_u32_b32 v8, -1, 0
	v_mbcnt_hi_u32_b32 v8, -1, v8
	s_lshr_b32 s49, s48, 8
	v_or_b32_e32 v0, s0, v8
	v_readlane_b32 s0, v255, 2
	v_readfirstlane_b32 s1, v0
	s_nop 0
	v_mov_b32_e32 v1, s0
	ds_read_b64 v[2:3], v1
	s_mul_i32 s0, s49, 52
	s_cmp_lt_i32 s46, s0
	s_cselect_b64 s[4:5], -1, 0
	s_cmp_ge_i32 s46, s0
	s_waitcnt lgkmcnt(0)
	v_readfirstlane_b32 s10, v3
	v_readfirstlane_b32 s11, v2
	s_cbranch_scc1 .LBB0_4216
	s_lshr_b32 s6, s0, 3
	v_readlane_b32 s7, v254, 33
	s_add_i32 s6, s6, s7
	v_readlane_b32 s7, v254, 32
	s_mul_i32 s6, s6, s7
	v_readlane_b32 s7, v254, 29
	s_sub_i32 s12, 0, s6
	s_and_b32 s12, s12, 3
	s_add_i32 s7, s7, s12
	s_lshr_b32 s12, s0, 3
	s_cmp_ge_u32 s7, s12
	s_cselect_b32 s12, s12, 0
	s_sub_i32 s7, s7, s12
	s_add_i32 s6, s6, s7
	s_mul_hi_i32 s7, s6, 0x4ec4ec4f
	s_lshr_b32 s12, s7, 31
	s_ashr_i32 s7, s7, 6
	s_add_i32 s7, s7, s12
	s_lshl_b32 s12, s7, 2
	s_sub_i32 s13, s49, s12
	s_min_i32 s13, s13, 4
	s_sext_i32_i16 s14, s13
	v_cvt_f32_i32_e32 v1, s14
	s_mulk_i32 s7, 0xd0
	s_sub_i32 s15, s6, s7
	v_cvt_f32_i32_e32 v2, s15
	v_rcp_iflag_f32_e32 v3, v1
	s_xor_b32 s6, s15, s14
	s_ashr_i32 s6, s6, 30
	s_or_b32 s14, s6, 1
	v_mul_f32_e32 v3, v2, v3
	v_trunc_f32_e32 v3, v3
	v_fma_f32 v2, -v3, v1, v2
	v_cvt_i32_f32_e32 v3, v3
	v_cmp_ge_f32_e64 s[6:7], |v2|, |v1|
	s_and_b64 s[6:7], s[6:7], exec
	s_cselect_b32 s6, s14, 0
	v_readfirstlane_b32 s7, v3
	s_add_i32 s6, s7, s6
	s_sext_i32_i16 s18, s6
	s_mul_i32 s6, s6, s13
	s_sub_i32 s6, s15, s6
	s_sext_i32_i16 s6, s6
	s_add_i32 s30, s12, s6

;     __host__ __device__ bool next(int i, Unit& u) const {
;         const long L = (long)i * G + c; if (L >= nwg) return false;
;         int wgid = (int)L; { const int q = nwg / NXCD, r = nwg % NXCD, xcd = wgid % NXCD, off = wgid / NXCD; wgid = (xcd < r ? xcd * (q + 1) : r * (q + 1) + (xcd - r) * q) + off; }
;         const int nig = WGM * nN, gid = wgid / nig, fm = gid * WGM, gsz = (nM - fm) < WGM ? (nM - fm) : WGM;
;         u.pm = fm + ((wgid % nig) % gsz); u.pn = (wgid % nig) / gsz; return true;
; template <class Epi>
; __device__ __forceinline__ void gemm_phase(const int tid, LAS unsigned char* lds, const Gemm g, const StaticOrder& S, const Epi& E) {
;     ...
;         const bool has_next = S.next(ui + 1, nxt);
;         const char* nA = has_next ? (const char*)g.A + (size_t)nxt.pm * tstepA : cA; const char* nB = has_next ? (const char*)g.Bt + (size_t)nxt.pn * tstepB : cB;
.LBB0_4222:
	s_add_i32 s66, s66, 1
	v_readlane_b32 s13, v253, 17
	v_readlane_b32 s14, v253, 0
	s_mul_i32 s13, s66, s13
	s_mov_b32 s26, s14
	s_mul_hi_u32 s14, s66, s14
	s_add_i32 s14, s14, s13
	s_mul_i32 s13, s66, s26
	s_add_u32 s34, s13, s46
	s_addc_u32 s35, s14, s47
	v_mov_b64_e32 v[0:1], s[0:1]
	v_cmp_ge_i64_e32 vcc, s[34:35], v[0:1]
	v_cmp_lt_i64_e64 s[36:37], s[34:35], v[0:1]
	v_readlane_b32 s15, v253, 1
	s_cbranch_vccnz .LBB0_4224
	s_ashr_i32 s13, s34, 31
	s_lshr_b32 s13, s13, 29
	s_add_i32 s13, s34, s13
	s_ashr_i32 s14, s13, 3
	s_and_b32 s13, s13, -8
	s_sub_i32 s13, s34, s13
	s_lshr_b32 s15, s13, 31
	s_add_i32 s15, s63, s15
	s_mul_i32 s13, s15, s13
	s_sub_i32 s15, 0, s13
	s_and_b32 s15, s15, 3
	s_add_i32 s14, s14, s15
	s_cmp_ge_u32 s14, s63
	s_cselect_b32 s15, s63, 0
	s_sub_i32 s14, s14, s15
	s_add_i32 s13, s13, s14
	s_mul_hi_i32 s14, s13, 0x4ec4ec4f
	s_lshr_b32 s15, s14, 31
	s_ashr_i32 s14, s14, 6
	s_add_i32 s14, s14, s15
	s_lshl_b32 s15, s14, 2
	s_sub_i32 s19, s49, s15
	s_min_i32 s19, s19, 4
	s_abs_i32 s26, s19
	v_cvt_f32_u32_e32 v0, s26
	s_sub_i32 s35, 0, s26
	s_mulk_i32 s14, 0xd0
	s_sub_i32 s13, s13, s14
	v_rcp_iflag_f32_e32 v0, v0
	s_abs_i32 s14, s13
	s_xor_b32 s34, s13, s19
	s_ashr_i32 s34, s34, 31
	v_mul_f32_e32 v0, 0x4f7ffffe, v0
	v_cvt_u32_f32_e32 v0, v0
	s_nop 0
	v_readfirstlane_b32 s38, v0
	s_mul_i32 s35, s35, s38
	s_mul_hi_u32 s35, s38, s35
	s_add_i32 s38, s38, s35
	s_mul_hi_u32 s35, s14, s38
	s_mul_i32 s38, s35, s26
	s_sub_i32 s14, s14, s38
	s_add_i32 s39, s35, 1
	s_sub_i32 s38, s14, s26
	s_cmp_ge_u32 s14, s26
	s_cselect_b32 s35, s39, s35
	s_cselect_b32 s14, s38, s14
	s_add_i32 s38, s35, 1
	s_cmp_ge_u32 s14, s26
	s_cselect_b32 s14, s38, s35
	s_xor_b32 s14, s14, s34
	s_sub_i32 s40, s14, s34
	s_mul_i32 s14, s40, s19
	s_sub_i32 s13, s13, s14
	s_add_i32 s42, s13, s15

;     __host__ __device__ bool next(int i, Unit& u) const {
;         const long L = (long)i * G + c; if (L >= nwg) return false;
;         int wgid = (int)L; { const int q = nwg / NXCD, r = nwg % NXCD, xcd = wgid % NXCD, off = wgid / NXCD; wgid = (xcd < r ? xcd * (q + 1) : r * (q + 1) + (xcd - r) * q) + off; }
;         const int nig = WGM * nN, gid = wgid / nig, fm = gid * WGM, gsz = (nM - fm) < WGM ? (nM - fm) : WGM;
;         u.pm = fm + ((wgid % nig) % gsz); u.pn = (wgid % nig) / gsz; return true;
; template <class Epi>
; __device__ __forceinline__ void gemm_phase(const int tid, LAS unsigned char* lds, const Gemm g, const StaticOrder& S, const Epi& E) {
;     ...
;         const bool has_next = S.next(ui + 1, nxt);
;         const char* nA = has_next ? (const char*)g.A + (size_t)nxt.pm * tstepA : cA; const char* nB = has_next ? (const char*)g.Bt + (size_t)nxt.pn * tstepB : cB;
.LBB0_5493:
	s_add_i32 s70, s70, 1
	v_readlane_b32 s5, v253, 17
	v_readlane_b32 s34, v253, 0
	s_mul_i32 s5, s70, s5
	s_mul_hi_u32 s19, s70, s34
	s_add_i32 s19, s19, s5
	s_mul_i32 s5, s70, s34
	v_readlane_b32 s35, v253, 1
	s_add_u32 s34, s5, s46
	s_addc_u32 s35, s19, s47
	v_mov_b64_e32 v[0:1], 0x1658
	v_cmp_lt_i64_e64 s[36:37], s[34:35], v[0:1]
	v_mov_b64_e32 v[0:1], 0x1657
	v_cmp_gt_i64_e32 vcc, s[34:35], v[0:1]
	s_cbranch_vccnz .LBB0_5495
	s_ashr_i32 s5, s34, 31
	s_lshr_b32 s5, s5, 29
	s_add_i32 s5, s34, s5
	s_ashr_i32 s19, s5, 3
	s_and_b32 s5, s5, -8
	s_sub_i32 s5, s34, s5
	s_cmp_lt_i32 s5, 0
	s_movk_i32 s34, 0x2cc
	s_cselect_b32 s34, s34, 0x2cb
	s_mul_i32 s5, s5, s34
	s_sub_i32 s35, 0, s5
	s_and_b32 s35, s35, 3
	s_add_i32 s19, s19, s35
	s_cmp_ge_u32 s19, s34
	s_cselect_b32 s35, s34, 0
	s_sub_i32 s19, s19, s35
	s_add_i32 s5, s5, s19
	s_mul_hi_i32 s19, s5, 0x2e8ba2e9
	s_lshr_b32 s34, s19, 31
	s_ashr_i32 s19, s19, 5
	s_add_i32 s19, s19, s34
	s_lshl_b32 s34, s19, 2
	s_sub_i32 s35, 0x82, s34
	s_min_i32 s35, s35, 4
	s_abs_i32 s42, s35
	v_cvt_f32_u32_e32 v0, s42
	s_sub_i32 s44, 0, s42
	s_mulk_i32 s19, 0xb0
	s_sub_i32 s5, s5, s19
	v_rcp_iflag_f32_e32 v0, v0
	s_abs_i32 s19, s5
	s_xor_b32 s43, s5, s35
	s_ashr_i32 s43, s43, 31
	v_mul_f32_e32 v0, 0x4f7ffffe, v0
	v_cvt_u32_f32_e32 v0, v0
	s_nop 0
	v_readfirstlane_b32 s45, v0
	s_mul_i32 s44, s44, s45
	s_mul_hi_u32 s44, s45, s44
	s_add_i32 s45, s45, s44
	s_mul_hi_u32 s44, s19, s45
	s_mul_i32 s45, s44, s42
	s_sub_i32 s19, s19, s45
	s_add_i32 s46, s44, 1
	s_sub_i32 s45, s19, s42
	s_cmp_ge_u32 s19, s42
	s_cselect_b32 s44, s46, s44
	s_cselect_b32 s19, s45, s19
	s_add_i32 s45, s44, 1
	s_cmp_ge_u32 s19, s42
	s_cselect_b32 s19, s45, s44
	s_xor_b32 s19, s19, s43
	s_sub_i32 s42, s19, s43
	s_mul_i32 s19, s42, s35
	s_sub_i32 s5, s5, s19
	s_add_i32 s44, s34, s5
